# pool phase: workgroup's 47 ZP rows staged into LDS by LDS-DMA, the 16 dependent global loads of the sliding window become LDS reads (on einv version)
# baseline (speedup 1.0000x reference)
; __device__ __forceinline__ size_t oq(size_t c) { asm volatile("" : "+s"(c)); return c; }
; #define PHASE_IDS() const int tid = opaque_tid(), lane = tid & 63, wave = __builtin_amdgcn_readfirstlane(tid >> 6); (void)lane; (void)wave
; __device__ __forceinline__ void p_pool(Frame& F) {
;     PHASE_IDS();
;     const bf16_t* ZP = (const bf16_t*)(F.ws + oq(WS_ZP)); bf16_t* PO = (bf16_t*)(F.ws + oq(WS_POOLED));
;     for (int id = F.vcu * 512 + tid; id < (MROWS / 8) * 128; id += F.G * 512) {
;         const int cg = id & 127, run = id >> 7, r0 = run * 8, t0 = r0 & (SEQ - 1), w = 2 << (cg >> 5);
;         f32x4 s0 = {0.f, 0.f, 0.f, 0.f}, s1 = {0.f, 0.f, 0.f, 0.f};
;         for (int j = 1; j < w; ++j) if (t0 - j >= 0) { f32x4 a, b; ld_bf16x8(ZP + (size_t)(r0 - j) * PD + 8 * cg, a, b); s0 += a; s1 += b; }
; #pragma unroll
;         for (int i = 0; i < 8; ++i) { const int t = t0 + i; f32x4 a, b; ld_bf16x8(ZP + (size_t)(r0 + i) * PD + 8 * cg, a, b); s0 += a; s1 += b;
;             const float inv = 1.0f / (float)((t + 1) < w ? (t + 1) : w);
;             st_bf16x8(PO + (size_t)(r0 + i) * PD + 8 * cg, s0 * inv - a, s1 * inv - b);
;             if (t - w + 1 >= 0) { f32x4 c, d; ld_bf16x8(ZP + (size_t)(r0 + i - w + 1) * PD + 8 * cg, c, d); s0 -= c; s1 -= d; } }
;     }
.LBB0_588:
	s_andn2_b64 vcc, exec, s[0:1]
	s_cbranch_vccnz .LBB0_674
	v_mov_b32_e32 v2, v0
	v_readlane_b32 s0, v245, 57
	s_mov_b64 s[4:5], 0x28000000
	s_mov_b64 s[6:7], 0x33000000
	s_waitcnt vmcnt(0)
	v_add_u32_e32 v26, s0, v2
	s_lshr_b32 s14, s0, 4
	s_and_b32 s16, s14, 0x7ff
	s_lshl_b32 s14, s14, 11
	s_add_u32 s14, s14, 0x27ff8800
	s_add_u32 s100, s54, s14
	s_addc_u32 s101, s55, 0
	v_lshrrev_b32_e32 v4, 6, v2
	v_and_b32_e32 v5, 63, v2
	v_readfirstlane_b32 s15, v4
	v_lshlrev_b32_e32 v5, 4, v5
	v_lshl_add_u32 v5, v4, 10, v5
	s_nop 3
	s_lshl_b32 s15, s15, 10
	s_mov_b32 s14, m0
	s_cmp_lg_u32 s16, 0
	s_cbranch_scc1 .Lpool_full
	v_add_u32_e32 v5, 0x6000, v5
	s_cmp_ge_u32 s15, 0x1800
	s_cbranch_scc1 .Lpool_q3
	v_add_u32_e32 v5, 0x2000, v5
	s_branch .Lpool_q4
.Lpool_full:
	s_add_i32 m0, s15, 0x0
	s_nop 0
	global_load_lds_dwordx4 v5, s[100:101]
	v_add_u32_e32 v5, 0x2000, v5
	s_add_i32 m0, s15, 0x2000
	s_nop 0
	global_load_lds_dwordx4 v5, s[100:101]
	v_add_u32_e32 v5, 0x2000, v5
	s_add_i32 m0, s15, 0x4000
	s_nop 0
	global_load_lds_dwordx4 v5, s[100:101]
	v_add_u32_e32 v5, 0x2000, v5
.Lpool_q3:
	s_add_i32 m0, s15, 0x6000
	s_nop 0
	global_load_lds_dwordx4 v5, s[100:101]
	v_add_u32_e32 v5, 0x2000, v5
.Lpool_q4:
	s_add_i32 m0, s15, 0x8000
	s_nop 0
	global_load_lds_dwordx4 v5, s[100:101]
	v_add_u32_e32 v5, 0x2000, v5
	s_add_i32 m0, s15, 0xa000
	s_nop 0
	global_load_lds_dwordx4 v5, s[100:101]
	v_add_u32_e32 v5, 0x2000, v5
	s_add_i32 m0, s15, 0xc000
	s_nop 0
	global_load_lds_dwordx4 v5, s[100:101]
	v_add_u32_e32 v5, 0x2000, v5
	s_add_i32 m0, s15, 0xe000
	s_nop 0
	global_load_lds_dwordx4 v5, s[100:101]
	v_add_u32_e32 v5, 0x2000, v5
	s_add_i32 m0, s15, 0x10000
	s_nop 0
	global_load_lds_dwordx4 v5, s[100:101]
	v_add_u32_e32 v5, 0x2000, v5
	s_add_i32 m0, s15, 0x12000
	s_nop 0
	global_load_lds_dwordx4 v5, s[100:101]
	v_add_u32_e32 v5, 0x2000, v5
	s_add_i32 m0, s15, 0x14000
	s_nop 0
	global_load_lds_dwordx4 v5, s[100:101]
	v_add_u32_e32 v5, 0x2000, v5
	s_cmp_lt_u32 s15, 0x1800
	s_cbranch_scc0 .Lpool_staged
	s_add_i32 m0, s15, 0x16000
	s_nop 0
	global_load_lds_dwordx4 v5, s[100:101]
	v_add_u32_e32 v5, 0x2000, v5
.Lpool_staged:
	s_mov_b32 m0, s14
	s_waitcnt vmcnt(0)
	s_barrier
	s_mov_b32 s0, 0x20000
	v_cmp_gt_i32_e32 vcc, s0, v26
	s_and_saveexec_b64 s[0:1], vcc
	v_readlane_b32 s17, v245, 58
	s_cbranch_execz .LBB0_610
	s_add_u32 s6, s54, s6
	s_addc_u32 s7, s55, s7
	s_waitcnt lgkmcnt(0)
	v_and_b32_e32 v4, 0x7f, v2
	v_bfe_u32 v2, v2, 5, 2
	s_add_u32 s14, s54, s4
	v_lshlrev_b32_e64 v27, v2, 2
	v_lshlrev_b32_e32 v2, 4, v4
	s_addc_u32 s15, s55, s5
	v_lshl_add_u64 v[16:17], s[6:7], 0, v[2:3]
	v_readlane_b32 s6, v243, 59
	s_add_u32 s4, s6, s4
	v_readlane_b32 s6, v243, 60
	s_addc_u32 s5, s6, s5
	v_lshl_add_u64 v[14:15], s[14:15], 0, v[2:3]
	v_add_u32_e32 v28, -2, v27
	v_lshl_add_u64 v[18:19], s[4:5], 0, v[2:3]
	s_mov_b64 s[4:5], 0
	s_branch .LBB0_592
.LBB0_591:
	s_or_b64 exec, exec, s[6:7]
	v_or_b32_e32 v12, 7, v30
	v_ashrrev_i32_e32 v13, 31, v12
	v_lshlrev_b64 v[12:13], 11, v[12:13]
	v_lshl_add_u64 v[20:21], v[14:15], 0, v[12:13]
	v_subrev_u32_e32 v20, s100, v20
	ds_read_b128 v[20:23], v20
	v_add_u32_e32 v2, 8, v29
	v_min_u32_e32 v2, v2, v27
	v_cvt_f32_ubyte0_e32 v2, v2
	v_div_scale_f32 v29, s[6:7], v2, v2, 1.0
	v_rcp_f32_e32 v32, v29
	v_add_u32_e32 v26, s17, v26
	s_mov_b32 s6, 0x1ffff
	v_lshl_add_u64 v[12:13], v[16:17], 0, v[12:13]
	v_fma_f32 v33, -v29, v32, 1.0
	v_fmac_f32_e32 v32, v33, v32
	v_div_scale_f32 v33, vcc, 1.0, v2, 1.0
	v_mul_f32_e32 v34, v33, v32
	v_fma_f32 v35, -v29, v34, v33
	v_fmac_f32_e32 v34, v35, v32
	v_fma_f32 v29, -v29, v34, v33
	v_div_fmas_f32 v29, v29, v32, v34
	v_div_fixup_f32 v2, v29, v2, 1.0
	v_cmp_lt_i32_e32 vcc, s6, v26
	s_or_b64 s[4:5], vcc, s[4:5]
	s_waitcnt lgkmcnt(0)
	v_lshlrev_b32_e32 v24, 16, v20
	v_and_b32_e32 v25, 0xffff0000, v20
	v_lshlrev_b32_e32 v20, 16, v21
	v_and_b32_e32 v21, 0xffff0000, v21
	v_pk_add_f32 v[4:5], v[4:5], v[20:21]
	v_xor_b32_e32 v21, 0x80000000, v21
	v_xor_b32_e32 v20, 0x80000000, v20
	v_lshlrev_b32_e32 v30, 16, v22
	v_and_b32_e32 v31, 0xffff0000, v22
	v_lshlrev_b32_e32 v22, 16, v23
	v_and_b32_e32 v23, 0xffff0000, v23
	v_pk_add_f32 v[8:9], v[8:9], v[24:25]
	v_pk_fma_f32 v[20:21], v[2:3], v[4:5], v[20:21] op_sel_hi:[0,1,1]
	v_xor_b32_e32 v5, 0x80000000, v25
	v_xor_b32_e32 v4, 0x80000000, v24
	v_pk_add_f32 v[6:7], v[6:7], v[22:23]
	v_pk_fma_f32 v[4:5], v[2:3], v[8:9], v[4:5] op_sel_hi:[0,1,1]
	v_xor_b32_e32 v9, 0x80000000, v23
	v_xor_b32_e32 v8, 0x80000000, v22
	v_pk_add_f32 v[10:11], v[10:11], v[30:31]
	v_pk_fma_f32 v[8:9], v[2:3], v[6:7], v[8:9] op_sel_hi:[0,1,1]
	v_xor_b32_e32 v7, 0x80000000, v31
	v_xor_b32_e32 v6, 0x80000000, v30
	v_pk_fma_f32 v[6:7], v[2:3], v[10:11], v[6:7] op_sel_hi:[0,1,1]
	v_cvt_pk_bf16_f32 v4, v4, v5
	v_cvt_pk_bf16_f32 v5, v20, v21
	v_cvt_pk_bf16_f32 v6, v6, v7
	v_cvt_pk_bf16_f32 v7, v8, v9
	global_store_dwordx4 v[12:13], v[4:7], off
	s_andn2_b64 exec, exec, s[4:5]
	s_cbranch_execz .LBB0_610

; __device__ __forceinline__ void p_pool(Frame& F) {
;     ...
;         for (int j = 1; j < w; ++j) if (t0 - j >= 0) { f32x4 a, b; ld_bf16x8(ZP + (size_t)(r0 - j) * PD + 8 * cg, a, b); s0 += a; s1 += b; }
; #pragma unroll
;         for (int i = 0; i < 8; ++i) { const int t = t0 + i; f32x4 a, b; ld_bf16x8(ZP + (size_t)(r0 + i) * PD + 8 * cg, a, b); s0 += a; s1 += b;
;             const float inv = 1.0f / (float)((t + 1) < w ? (t + 1) : w);
;             st_bf16x8(PO + (size_t)(r0 + i) * PD + 8 * cg, s0 * inv - a, s1 * inv - b);
;             if (t - w + 1 >= 0) { f32x4 c, d; ld_bf16x8(ZP + (size_t)(r0 + i - w + 1) * PD + 8 * cg, c, d); s0 -= c; s1 -= d; } }
.LBB0_594:
	v_cmp_le_u32_e32 vcc, s16, v29
	s_and_saveexec_b64 s[14:15], vcc
	s_cbranch_execz .LBB0_593
	v_subrev_u32_e32 v32, s100, v22
	ds_read_b128 v[32:35], v32
	s_waitcnt lgkmcnt(0)
	v_lshlrev_b32_e32 v4, 16, v32
	v_and_b32_e32 v5, 0xffff0000, v32
	v_lshlrev_b32_e32 v32, 16, v33
	v_and_b32_e32 v33, 0xffff0000, v33
	v_lshlrev_b32_e32 v36, 16, v34
	v_and_b32_e32 v37, 0xffff0000, v34
	v_lshlrev_b32_e32 v34, 16, v35
	v_and_b32_e32 v35, 0xffff0000, v35
	v_pk_add_f32 v[12:13], v[12:13], v[32:33]
	v_pk_add_f32 v[10:11], v[10:11], v[4:5]
	v_pk_add_f32 v[8:9], v[8:9], v[34:35]
	v_pk_add_f32 v[6:7], v[6:7], v[36:37]
	s_branch .LBB0_593
.LBB0_596:
	s_or_b64 exec, exec, s[6:7]
	v_lshl_add_u64 v[4:5], v[14:15], 0, v[24:25]
	v_subrev_u32_e32 v32, s100, v4
	ds_read_b128 v[32:35], v32
	v_or_b32_e32 v2, 1, v29
	v_min_u32_e32 v2, v2, v27
	v_cvt_f32_ubyte0_e32 v2, v2
	s_waitcnt lgkmcnt(0)
	v_lshlrev_b32_e32 v36, 16, v32
	v_and_b32_e32 v37, 0xffff0000, v32
	v_pk_add_f32 v[4:5], v[10:11], v[36:37]
	v_div_scale_f32 v10, s[6:7], v2, v2, 1.0
	v_rcp_f32_e32 v11, v10
	v_lshlrev_b32_e32 v32, 16, v33
	v_and_b32_e32 v33, 0xffff0000, v33
	v_lshlrev_b32_e32 v22, 16, v34
	v_fma_f32 v21, -v10, v11, 1.0
	v_fmac_f32_e32 v11, v21, v11
	v_div_scale_f32 v21, vcc, 1.0, v2, 1.0
	v_mul_f32_e32 v31, v21, v11
	v_fma_f32 v38, -v10, v31, v21
	v_fmac_f32_e32 v31, v38, v11
	v_fma_f32 v10, -v10, v31, v21
	v_and_b32_e32 v23, 0xffff0000, v34
	v_lshlrev_b32_e32 v34, 16, v35
	v_and_b32_e32 v35, 0xffff0000, v35
	v_div_fmas_f32 v10, v10, v11, v31
	v_pk_add_f32 v[12:13], v[12:13], v[32:33]
	v_pk_add_f32 v[8:9], v[8:9], v[34:35]
	v_pk_add_f32 v[6:7], v[6:7], v[22:23]
	v_div_fixup_f32 v2, v10, v2, 1.0
	v_lshl_add_u64 v[10:11], v[16:17], 0, v[24:25]
	v_xor_b32_e32 v25, 0x80000000, v33
	v_xor_b32_e32 v24, 0x80000000, v32
	v_xor_b32_e32 v33, 0x80000000, v37
	v_xor_b32_e32 v32, 0x80000000, v36
	v_xor_b32_e32 v35, 0x80000000, v35
	v_xor_b32_e32 v34, 0x80000000, v34
	v_xor_b32_e32 v23, 0x80000000, v23
	v_xor_b32_e32 v22, 0x80000000, v22
	v_pk_fma_f32 v[24:25], v[2:3], v[12:13], v[24:25] op_sel_hi:[0,1,1]
	v_pk_fma_f32 v[32:33], v[2:3], v[4:5], v[32:33] op_sel_hi:[0,1,1]
	v_pk_fma_f32 v[34:35], v[2:3], v[8:9], v[34:35] op_sel_hi:[0,1,1]
	v_pk_fma_f32 v[36:37], v[2:3], v[6:7], v[22:23] op_sel_hi:[0,1,1]
	v_cvt_pk_bf16_f32 v22, v32, v33
	v_cvt_pk_bf16_f32 v23, v24, v25
	v_cvt_pk_bf16_f32 v24, v36, v37
	v_cvt_pk_bf16_f32 v25, v34, v35
	v_cmp_ge_u32_e32 vcc, v29, v27
	global_store_dwordx4 v[10:11], v[22:25], off
	s_and_saveexec_b64 s[6:7], vcc
	s_cbranch_execz .LBB0_598
	v_sub_u32_e32 v2, v20, v27
	v_or_b32_e32 v10, 1, v2
	v_ashrrev_i32_e32 v11, 31, v10
	v_lshlrev_b64 v[10:11], 11, v[10:11]
	v_lshl_add_u64 v[10:11], v[14:15], 0, v[10:11]
	v_subrev_u32_e32 v22, s100, v10
	ds_read_b128 v[22:25], v22
	s_waitcnt lgkmcnt(0)
	v_lshlrev_b32_e32 v2, 16, v22
	v_and_b32_e32 v10, 0xffff0000, v22
	v_lshlrev_b32_e32 v11, 16, v23
	v_and_b32_e32 v21, 0xffff0000, v23
	v_lshlrev_b32_e32 v22, 16, v24
	v_and_b32_e32 v23, 0xffff0000, v24
	v_lshlrev_b32_e32 v24, 16, v25
	v_and_b32_e32 v25, 0xffff0000, v25
	v_sub_f32_e32 v13, v13, v21
	v_sub_f32_e32 v12, v12, v11
	v_sub_f32_e32 v5, v5, v10
	v_sub_f32_e32 v4, v4, v2
	v_sub_f32_e32 v9, v9, v25
	v_sub_f32_e32 v8, v8, v24
	v_sub_f32_e32 v7, v7, v23
	v_sub_f32_e32 v6, v6, v22
.LBB0_598:
	s_or_b64 exec, exec, s[6:7]
	v_or_b32_e32 v22, 1, v20
	v_ashrrev_i32_e32 v23, 31, v22
	v_lshlrev_b64 v[24:25], 11, v[22:23]
	v_lshl_add_u64 v[10:11], v[14:15], 0, v[24:25]
	v_subrev_u32_e32 v32, s100, v10
	ds_read_b128 v[32:35], v32
	v_or_b32_e32 v2, 2, v29
	v_min_u32_e32 v2, v2, v27
	v_cvt_f32_ubyte0_e32 v2, v2
	v_cmp_ge_i32_e64 s[40:41], v29, v28
	s_waitcnt lgkmcnt(0)
	v_lshlrev_b32_e32 v36, 16, v32
	v_and_b32_e32 v37, 0xffff0000, v32
	v_lshlrev_b32_e32 v32, 16, v33
	v_and_b32_e32 v33, 0xffff0000, v33
	v_lshlrev_b32_e32 v38, 16, v34
	v_and_b32_e32 v39, 0xffff0000, v34
	v_lshlrev_b32_e32 v34, 16, v35
	v_and_b32_e32 v35, 0xffff0000, v35
	v_pk_add_f32 v[10:11], v[12:13], v[32:33]
	v_pk_add_f32 v[12:13], v[4:5], v[36:37]
	v_pk_add_f32 v[4:5], v[8:9], v[34:35]
	v_pk_add_f32 v[8:9], v[6:7], v[38:39]
	v_div_scale_f32 v6, s[6:7], v2, v2, 1.0
	v_rcp_f32_e32 v7, v6
	v_xor_b32_e32 v35, 0x80000000, v35
	v_xor_b32_e32 v34, 0x80000000, v34
	v_fma_f32 v21, -v6, v7, 1.0
	v_fmac_f32_e32 v7, v21, v7
	v_div_scale_f32 v21, vcc, 1.0, v2, 1.0
	v_mul_f32_e32 v23, v21, v7
	v_fma_f32 v31, -v6, v23, v21
	v_fmac_f32_e32 v23, v31, v7
	v_fma_f32 v6, -v6, v23, v21
	v_div_fmas_f32 v6, v6, v7, v23
	v_div_fixup_f32 v2, v6, v2, 1.0
	v_lshl_add_u64 v[6:7], v[16:17], 0, v[24:25]
	v_xor_b32_e32 v25, 0x80000000, v33
	v_xor_b32_e32 v24, 0x80000000, v32
	v_xor_b32_e32 v33, 0x80000000, v37
	v_xor_b32_e32 v32, 0x80000000, v36
	v_pk_fma_f32 v[36:37], v[2:3], v[4:5], v[34:35] op_sel_hi:[0,1,1]
	v_xor_b32_e32 v35, 0x80000000, v39
	v_xor_b32_e32 v34, 0x80000000, v38
	v_pk_fma_f32 v[24:25], v[2:3], v[10:11], v[24:25] op_sel_hi:[0,1,1]
	v_pk_fma_f32 v[32:33], v[2:3], v[12:13], v[32:33] op_sel_hi:[0,1,1]
	v_pk_fma_f32 v[34:35], v[2:3], v[8:9], v[34:35] op_sel_hi:[0,1,1]
	v_cvt_pk_bf16_f32 v32, v32, v33
	v_cvt_pk_bf16_f32 v33, v24, v25
	v_cvt_pk_bf16_f32 v34, v34, v35
	v_cvt_pk_bf16_f32 v35, v36, v37
	global_store_dwordx4 v[6:7], v[32:35], off
	s_and_saveexec_b64 s[6:7], s[40:41]
	s_cbranch_execz .LBB0_600
	v_sub_u32_e32 v6, v22, v27
	v_ashrrev_i32_e32 v7, 31, v6
	v_lshlrev_b64 v[6:7], 11, v[6:7]
	v_lshl_add_u64 v[6:7], v[14:15], 0, v[6:7]
	v_subrev_u32_e32 v22, s100, v6
	ds_read_b128 v[22:25], v22 offset:2048
	s_waitcnt lgkmcnt(0)
	v_lshlrev_b32_e32 v2, 16, v22
	v_and_b32_e32 v6, 0xffff0000, v22
	v_lshlrev_b32_e32 v7, 16, v23
	v_and_b32_e32 v21, 0xffff0000, v23
	v_lshlrev_b32_e32 v22, 16, v24
	v_and_b32_e32 v23, 0xffff0000, v24
	v_lshlrev_b32_e32 v24, 16, v25
	v_and_b32_e32 v25, 0xffff0000, v25
	v_sub_f32_e32 v11, v11, v21
	v_sub_f32_e32 v10, v10, v7
	v_sub_f32_e32 v13, v13, v6
	v_sub_f32_e32 v12, v12, v2
	v_sub_f32_e32 v5, v5, v25
	v_sub_f32_e32 v4, v4, v24
	v_sub_f32_e32 v9, v9, v23
	v_sub_f32_e32 v8, v8, v22
; __device__ __forceinline__ void p_pool(Frame& F) {
;     ...
;         for (int i = 0; i < 8; ++i) { const int t = t0 + i; f32x4 a, b; ld_bf16x8(ZP + (size_t)(r0 + i) * PD + 8 * cg, a, b); s0 += a; s1 += b;
;             const float inv = 1.0f / (float)((t + 1) < w ? (t + 1) : w);
;             st_bf16x8(PO + (size_t)(r0 + i) * PD + 8 * cg, s0 * inv - a, s1 * inv - b);
;             if (t - w + 1 >= 0) { f32x4 c, d; ld_bf16x8(ZP + (size_t)(r0 + i - w + 1) * PD + 8 * cg, c, d); s0 -= c; s1 -= d; } }
.LBB0_600:
	s_or_b64 exec, exec, s[6:7]
	v_or_b32_e32 v22, 2, v20
	v_ashrrev_i32_e32 v23, 31, v22
	v_lshlrev_b64 v[24:25], 11, v[22:23]
	v_lshl_add_u64 v[6:7], v[14:15], 0, v[24:25]
	v_subrev_u32_e32 v32, s100, v6
	ds_read_b128 v[32:35], v32
	v_or_b32_e32 v2, 3, v29
	v_lshl_add_u64 v[24:25], v[16:17], 0, v[24:25]
	s_waitcnt lgkmcnt(0)
	v_lshlrev_b32_e32 v36, 16, v32
	v_and_b32_e32 v37, 0xffff0000, v32
	v_lshlrev_b32_e32 v32, 16, v33
	v_and_b32_e32 v33, 0xffff0000, v33
	v_pk_add_f32 v[6:7], v[10:11], v[32:33]
	v_pk_add_f32 v[10:11], v[12:13], v[36:37]
	v_min_u32_e32 v12, v2, v27
	v_cvt_f32_ubyte0_e32 v12, v12
	v_div_scale_f32 v13, s[6:7], v12, v12, 1.0
	v_rcp_f32_e32 v21, v13
	v_lshlrev_b32_e32 v38, 16, v34
	v_and_b32_e32 v39, 0xffff0000, v34
	v_lshlrev_b32_e32 v34, 16, v35
	v_fma_f32 v23, -v13, v21, 1.0
	v_fmac_f32_e32 v21, v23, v21
	v_div_scale_f32 v23, vcc, 1.0, v12, 1.0
	v_mul_f32_e32 v31, v23, v21
	v_fma_f32 v40, -v13, v31, v23
	v_fmac_f32_e32 v31, v40, v21
	v_fma_f32 v13, -v13, v31, v23
	v_and_b32_e32 v35, 0xffff0000, v35
	v_div_fmas_f32 v13, v13, v21, v31
	v_pk_add_f32 v[4:5], v[4:5], v[34:35]
	v_div_fixup_f32 v12, v13, v12, 1.0
	v_xor_b32_e32 v33, 0x80000000, v33
	v_xor_b32_e32 v32, 0x80000000, v32
	v_xor_b32_e32 v35, 0x80000000, v35
	v_xor_b32_e32 v34, 0x80000000, v34
	v_pk_add_f32 v[8:9], v[8:9], v[38:39]
	v_pk_fma_f32 v[40:41], v[12:13], v[6:7], v[32:33] op_sel_hi:[0,1,1]
	v_xor_b32_e32 v33, 0x80000000, v37
	v_xor_b32_e32 v32, 0x80000000, v36
	v_pk_fma_f32 v[36:37], v[12:13], v[4:5], v[34:35] op_sel_hi:[0,1,1]
	v_xor_b32_e32 v35, 0x80000000, v39
	v_xor_b32_e32 v34, 0x80000000, v38
	v_pk_fma_f32 v[32:33], v[12:13], v[10:11], v[32:33] op_sel_hi:[0,1,1]
	v_pk_fma_f32 v[12:13], v[12:13], v[8:9], v[34:35] op_sel_hi:[0,1,1]
	v_cvt_pk_bf16_f32 v32, v32, v33
	v_cvt_pk_bf16_f32 v33, v40, v41
	v_cvt_pk_bf16_f32 v34, v12, v13
	v_cvt_pk_bf16_f32 v35, v36, v37
	global_store_dwordx4 v[24:25], v[32:35], off
	s_and_saveexec_b64 s[6:7], s[40:41]
	s_cbranch_execz .LBB0_602
	v_sub_u32_e32 v12, v22, v27
	v_or_b32_e32 v12, 1, v12
	v_ashrrev_i32_e32 v13, 31, v12
	v_lshlrev_b64 v[12:13], 11, v[12:13]
	v_lshl_add_u64 v[12:13], v[14:15], 0, v[12:13]
	v_subrev_u32_e32 v22, s100, v12
	ds_read_b128 v[22:25], v22
	s_waitcnt lgkmcnt(0)
	v_lshlrev_b32_e32 v12, 16, v22
	v_and_b32_e32 v13, 0xffff0000, v22
	v_lshlrev_b32_e32 v21, 16, v23
	v_and_b32_e32 v22, 0xffff0000, v23
	v_lshlrev_b32_e32 v23, 16, v24
	v_and_b32_e32 v24, 0xffff0000, v24
	v_lshlrev_b32_e32 v31, 16, v25
	v_and_b32_e32 v25, 0xffff0000, v25
	v_sub_f32_e32 v7, v7, v22
	v_sub_f32_e32 v6, v6, v21
	v_sub_f32_e32 v11, v11, v13
	v_sub_f32_e32 v10, v10, v12
	v_sub_f32_e32 v5, v5, v25
	v_sub_f32_e32 v4, v4, v31
	v_sub_f32_e32 v9, v9, v24
	v_sub_f32_e32 v8, v8, v23
.LBB0_602:
	s_or_b64 exec, exec, s[6:7]
	v_or_b32_e32 v24, 3, v20
	v_ashrrev_i32_e32 v25, 31, v24
	v_lshlrev_b64 v[36:37], 11, v[24:25]
	v_lshl_add_u64 v[12:13], v[14:15], 0, v[36:37]
	v_subrev_u32_e32 v32, s100, v12
	ds_read_b128 v[32:35], v32
	v_or_b32_e32 v21, 4, v29
	s_waitcnt lgkmcnt(0)
	v_lshlrev_b32_e32 v38, 16, v32
	v_and_b32_e32 v39, 0xffff0000, v32
	v_lshlrev_b32_e32 v40, 16, v34
	v_and_b32_e32 v41, 0xffff0000, v34
	v_lshlrev_b32_e32 v34, 16, v35
	v_and_b32_e32 v35, 0xffff0000, v35
	v_pk_add_f32 v[12:13], v[10:11], v[38:39]
	v_pk_add_f32 v[10:11], v[4:5], v[34:35]
	v_min_u32_e32 v4, v21, v27
	v_cvt_f32_ubyte0_e32 v4, v4
	v_div_scale_f32 v5, s[6:7], v4, v4, 1.0
	v_pk_add_f32 v[22:23], v[8:9], v[40:41]
	v_rcp_f32_e32 v8, v5
	v_lshlrev_b32_e32 v32, 16, v33
	v_and_b32_e32 v33, 0xffff0000, v33
	v_pk_add_f32 v[6:7], v[6:7], v[32:33]
	v_fma_f32 v9, -v5, v8, 1.0
	v_fmac_f32_e32 v8, v9, v8
	v_div_scale_f32 v9, vcc, 1.0, v4, 1.0
	v_mul_f32_e32 v25, v9, v8
	v_fma_f32 v31, -v5, v25, v9
	v_fmac_f32_e32 v25, v31, v8
	v_fma_f32 v5, -v5, v25, v9
	v_div_fmas_f32 v5, v5, v8, v25
	v_div_fixup_f32 v4, v5, v4, 1.0
	v_xor_b32_e32 v33, 0x80000000, v33
	v_xor_b32_e32 v32, 0x80000000, v32
	v_xor_b32_e32 v35, 0x80000000, v35
	v_xor_b32_e32 v34, 0x80000000, v34
	v_lshl_add_u64 v[8:9], v[16:17], 0, v[36:37]
	v_pk_fma_f32 v[36:37], v[4:5], v[6:7], v[32:33] op_sel_hi:[0,1,1]
	v_xor_b32_e32 v33, 0x80000000, v39
	v_xor_b32_e32 v32, 0x80000000, v38
	v_pk_fma_f32 v[38:39], v[4:5], v[10:11], v[34:35] op_sel_hi:[0,1,1]
	v_xor_b32_e32 v35, 0x80000000, v41
	v_xor_b32_e32 v34, 0x80000000, v40
	v_pk_fma_f32 v[32:33], v[4:5], v[12:13], v[32:33] op_sel_hi:[0,1,1]
	v_pk_fma_f32 v[4:5], v[4:5], v[22:23], v[34:35] op_sel_hi:[0,1,1]
	v_cvt_pk_bf16_f32 v32, v32, v33
	v_cvt_pk_bf16_f32 v33, v36, v37
	v_cvt_pk_bf16_f32 v34, v4, v5
	v_cvt_pk_bf16_f32 v35, v38, v39
	v_cmp_gt_i32_e32 vcc, v2, v28
	global_store_dwordx4 v[8:9], v[32:35], off
	s_and_saveexec_b64 s[6:7], vcc
	s_cbranch_execz .LBB0_604
	v_sub_u32_e32 v4, v24, v27
	v_ashrrev_i32_e32 v5, 31, v4
	v_lshlrev_b64 v[4:5], 11, v[4:5]
	v_lshl_add_u64 v[4:5], v[14:15], 0, v[4:5]
	v_subrev_u32_e32 v32, s100, v4
	ds_read_b128 v[32:35], v32 offset:2048
	s_waitcnt lgkmcnt(0)
	v_lshlrev_b32_e32 v2, 16, v32
	v_and_b32_e32 v4, 0xffff0000, v32
	v_lshlrev_b32_e32 v5, 16, v33
	v_and_b32_e32 v8, 0xffff0000, v33
	v_lshlrev_b32_e32 v9, 16, v34
	v_and_b32_e32 v24, 0xffff0000, v34
	v_lshlrev_b32_e32 v25, 16, v35
	v_and_b32_e32 v31, 0xffff0000, v35
	v_sub_f32_e32 v7, v7, v8
	v_sub_f32_e32 v6, v6, v5
	v_sub_f32_e32 v13, v13, v4
	v_sub_f32_e32 v12, v12, v2
	v_sub_f32_e32 v11, v11, v31
	v_sub_f32_e32 v10, v10, v25
	v_sub_f32_e32 v23, v23, v24
	v_sub_f32_e32 v22, v22, v9
; __device__ __forceinline__ void p_pool(Frame& F) {
;     ...
;         for (int i = 0; i < 8; ++i) { const int t = t0 + i; f32x4 a, b; ld_bf16x8(ZP + (size_t)(r0 + i) * PD + 8 * cg, a, b); s0 += a; s1 += b;
;             const float inv = 1.0f / (float)((t + 1) < w ? (t + 1) : w);
;             st_bf16x8(PO + (size_t)(r0 + i) * PD + 8 * cg, s0 * inv - a, s1 * inv - b);
;             if (t - w + 1 >= 0) { f32x4 c, d; ld_bf16x8(ZP + (size_t)(r0 + i - w + 1) * PD + 8 * cg, c, d); s0 -= c; s1 -= d; } }
.LBB0_604:
	s_or_b64 exec, exec, s[6:7]
	v_or_b32_e32 v24, 4, v20
	v_ashrrev_i32_e32 v25, 31, v24
	v_lshlrev_b64 v[36:37], 11, v[24:25]
	v_lshl_add_u64 v[4:5], v[14:15], 0, v[36:37]
	v_subrev_u32_e32 v32, s100, v4
	ds_read_b128 v[32:35], v32
	v_or_b32_e32 v2, 5, v29
	s_waitcnt lgkmcnt(0)
	v_lshlrev_b32_e32 v38, 16, v32
	v_and_b32_e32 v39, 0xffff0000, v32
	v_pk_add_f32 v[8:9], v[12:13], v[38:39]
	v_min_u32_e32 v12, v2, v27
	v_cvt_f32_ubyte0_e32 v12, v12
	v_lshlrev_b32_e32 v32, 16, v33
	v_and_b32_e32 v33, 0xffff0000, v33
	v_lshlrev_b32_e32 v40, 16, v34
	v_and_b32_e32 v41, 0xffff0000, v34
	v_lshlrev_b32_e32 v34, 16, v35
	v_and_b32_e32 v35, 0xffff0000, v35
	v_div_scale_f32 v13, s[6:7], v12, v12, 1.0
	v_pk_add_f32 v[4:5], v[6:7], v[32:33]
	v_pk_add_f32 v[6:7], v[10:11], v[34:35]
	v_pk_add_f32 v[10:11], v[22:23], v[40:41]
	v_rcp_f32_e32 v22, v13
	v_xor_b32_e32 v33, 0x80000000, v33
	v_xor_b32_e32 v32, 0x80000000, v32
	v_xor_b32_e32 v35, 0x80000000, v35
	v_fma_f32 v23, -v13, v22, 1.0
	v_fmac_f32_e32 v22, v23, v22
	v_div_scale_f32 v23, vcc, 1.0, v12, 1.0
	v_mul_f32_e32 v25, v23, v22
	v_fma_f32 v31, -v13, v25, v23
	v_fmac_f32_e32 v25, v31, v22
	v_fma_f32 v13, -v13, v25, v23
	v_div_fmas_f32 v13, v13, v22, v25
	v_div_fixup_f32 v12, v13, v12, 1.0
	v_xor_b32_e32 v34, 0x80000000, v34
	v_lshl_add_u64 v[22:23], v[16:17], 0, v[36:37]
	v_pk_fma_f32 v[36:37], v[12:13], v[4:5], v[32:33] op_sel_hi:[0,1,1]
	v_xor_b32_e32 v33, 0x80000000, v39
	v_xor_b32_e32 v32, 0x80000000, v38
	v_pk_fma_f32 v[38:39], v[12:13], v[6:7], v[34:35] op_sel_hi:[0,1,1]
	v_xor_b32_e32 v35, 0x80000000, v41
	v_xor_b32_e32 v34, 0x80000000, v40
	v_pk_fma_f32 v[32:33], v[12:13], v[8:9], v[32:33] op_sel_hi:[0,1,1]
	v_pk_fma_f32 v[12:13], v[12:13], v[10:11], v[34:35] op_sel_hi:[0,1,1]
	v_cvt_pk_bf16_f32 v32, v32, v33
	v_cvt_pk_bf16_f32 v33, v36, v37
	v_cvt_pk_bf16_f32 v34, v12, v13
	v_cvt_pk_bf16_f32 v35, v38, v39
	v_cmp_ge_u32_e32 vcc, v21, v27
	global_store_dwordx4 v[22:23], v[32:35], off
	s_and_saveexec_b64 s[6:7], vcc
	s_cbranch_execz .LBB0_606
	v_sub_u32_e32 v12, v24, v27
	v_or_b32_e32 v12, 1, v12
	v_ashrrev_i32_e32 v13, 31, v12
	v_lshlrev_b64 v[12:13], 11, v[12:13]
	v_lshl_add_u64 v[12:13], v[14:15], 0, v[12:13]
	v_subrev_u32_e32 v22, s100, v12
	ds_read_b128 v[22:25], v22
	s_waitcnt lgkmcnt(0)
	v_lshlrev_b32_e32 v12, 16, v22
	v_and_b32_e32 v13, 0xffff0000, v22
	v_lshlrev_b32_e32 v21, 16, v23
	v_and_b32_e32 v22, 0xffff0000, v23
	v_lshlrev_b32_e32 v23, 16, v24
	v_and_b32_e32 v24, 0xffff0000, v24
	v_lshlrev_b32_e32 v31, 16, v25
	v_and_b32_e32 v25, 0xffff0000, v25
	v_sub_f32_e32 v5, v5, v22
	v_sub_f32_e32 v4, v4, v21
	v_sub_f32_e32 v9, v9, v13
	v_sub_f32_e32 v8, v8, v12
	v_sub_f32_e32 v7, v7, v25
	v_sub_f32_e32 v6, v6, v31
	v_sub_f32_e32 v11, v11, v24
	v_sub_f32_e32 v10, v10, v23
.LBB0_606:
	s_or_b64 exec, exec, s[6:7]
	v_or_b32_e32 v12, 5, v20
	v_ashrrev_i32_e32 v13, 31, v12
	v_lshlrev_b64 v[32:33], 11, v[12:13]
	v_lshl_add_u64 v[22:23], v[14:15], 0, v[32:33]
	v_subrev_u32_e32 v22, s100, v22
	ds_read_b128 v[22:25], v22
	v_or_b32_e32 v21, 6, v29
	v_min_u32_e32 v13, v21, v27
	v_cvt_f32_ubyte0_e32 v13, v13
	v_div_scale_f32 v31, s[6:7], v13, v13, 1.0
	v_rcp_f32_e32 v38, v31
	v_lshl_add_u64 v[32:33], v[16:17], 0, v[32:33]
	v_fma_f32 v39, -v31, v38, 1.0
	v_fmac_f32_e32 v38, v39, v38
	v_div_scale_f32 v39, vcc, 1.0, v13, 1.0
	v_mul_f32_e32 v40, v39, v38
	v_fma_f32 v41, -v31, v40, v39
	v_fmac_f32_e32 v40, v41, v38
	v_fma_f32 v31, -v31, v40, v39
	v_div_fmas_f32 v31, v31, v38, v40
	v_div_fixup_f32 v38, v31, v13, 1.0
	v_cmp_gt_i32_e32 vcc, v2, v28
	s_waitcnt lgkmcnt(0)
	v_lshlrev_b32_e32 v34, 16, v22
	v_and_b32_e32 v35, 0xffff0000, v22
	v_lshlrev_b32_e32 v22, 16, v23
	v_and_b32_e32 v23, 0xffff0000, v23
	v_lshlrev_b32_e32 v36, 16, v24
	v_and_b32_e32 v37, 0xffff0000, v24
	v_lshlrev_b32_e32 v24, 16, v25
	v_and_b32_e32 v25, 0xffff0000, v25
	v_pk_add_f32 v[4:5], v[4:5], v[22:23]
	v_pk_add_f32 v[6:7], v[6:7], v[24:25]
	v_xor_b32_e32 v23, 0x80000000, v23
	v_xor_b32_e32 v22, 0x80000000, v22
	v_xor_b32_e32 v25, 0x80000000, v25
	v_xor_b32_e32 v24, 0x80000000, v24
	v_pk_add_f32 v[8:9], v[8:9], v[34:35]
	v_pk_add_f32 v[10:11], v[10:11], v[36:37]
	v_pk_fma_f32 v[40:41], v[38:39], v[4:5], v[22:23] op_sel_hi:[0,1,1]
	v_xor_b32_e32 v23, 0x80000000, v35
	v_xor_b32_e32 v22, 0x80000000, v34
	v_pk_fma_f32 v[34:35], v[38:39], v[6:7], v[24:25] op_sel_hi:[0,1,1]
	v_xor_b32_e32 v25, 0x80000000, v37
	v_xor_b32_e32 v24, 0x80000000, v36
	v_pk_fma_f32 v[22:23], v[38:39], v[8:9], v[22:23] op_sel_hi:[0,1,1]
	v_pk_fma_f32 v[24:25], v[38:39], v[10:11], v[24:25] op_sel_hi:[0,1,1]
	v_cvt_pk_bf16_f32 v22, v22, v23
	v_cvt_pk_bf16_f32 v23, v40, v41
	v_cvt_pk_bf16_f32 v24, v24, v25
	v_cvt_pk_bf16_f32 v25, v34, v35
	global_store_dwordx4 v[32:33], v[22:25], off
	s_and_saveexec_b64 s[6:7], vcc
	s_cbranch_execz .LBB0_608
	v_sub_u32_e32 v12, v12, v27
	v_ashrrev_i32_e32 v13, 31, v12
	v_lshlrev_b64 v[12:13], 11, v[12:13]
	v_lshl_add_u64 v[12:13], v[14:15], 0, v[12:13]
	v_subrev_u32_e32 v22, s100, v12
	ds_read_b128 v[22:25], v22 offset:2048
	s_waitcnt lgkmcnt(0)
	v_lshlrev_b32_e32 v2, 16, v22
	v_and_b32_e32 v12, 0xffff0000, v22
	v_lshlrev_b32_e32 v13, 16, v23
	v_and_b32_e32 v22, 0xffff0000, v23
	v_lshlrev_b32_e32 v23, 16, v24
	v_and_b32_e32 v24, 0xffff0000, v24
	v_lshlrev_b32_e32 v31, 16, v25
	v_and_b32_e32 v25, 0xffff0000, v25
	v_sub_f32_e32 v5, v5, v22
	v_sub_f32_e32 v4, v4, v13
	v_sub_f32_e32 v9, v9, v12
	v_sub_f32_e32 v8, v8, v2
	v_sub_f32_e32 v7, v7, v25
	v_sub_f32_e32 v6, v6, v31
	v_sub_f32_e32 v11, v11, v24
	v_sub_f32_e32 v10, v10, v23
; __device__ __forceinline__ void p_pool(Frame& F) {
;     ...
;         for (int i = 0; i < 8; ++i) { const int t = t0 + i; f32x4 a, b; ld_bf16x8(ZP + (size_t)(r0 + i) * PD + 8 * cg, a, b); s0 += a; s1 += b;
;             const float inv = 1.0f / (float)((t + 1) < w ? (t + 1) : w);
;             st_bf16x8(PO + (size_t)(r0 + i) * PD + 8 * cg, s0 * inv - a, s1 * inv - b);
;             if (t - w + 1 >= 0) { f32x4 c, d; ld_bf16x8(ZP + (size_t)(r0 + i - w + 1) * PD + 8 * cg, c, d); s0 -= c; s1 -= d; } }
.LBB0_608:
	s_or_b64 exec, exec, s[6:7]
	v_or_b32_e32 v12, 6, v20
	v_ashrrev_i32_e32 v13, 31, v12
	v_lshlrev_b64 v[32:33], 11, v[12:13]
	v_lshl_add_u64 v[22:23], v[14:15], 0, v[32:33]
	v_subrev_u32_e32 v22, s100, v22
	ds_read_b128 v[22:25], v22
	v_or_b32_e32 v2, 7, v29
	v_min_u32_e32 v2, v2, v27
	v_cvt_f32_ubyte0_e32 v2, v2
	v_div_scale_f32 v13, s[6:7], v2, v2, 1.0
	v_rcp_f32_e32 v20, v13
	v_lshl_add_u64 v[32:33], v[16:17], 0, v[32:33]
	v_fma_f32 v31, -v13, v20, 1.0
	v_fmac_f32_e32 v20, v31, v20
	v_div_scale_f32 v31, vcc, 1.0, v2, 1.0
	v_mul_f32_e32 v38, v31, v20
	v_fma_f32 v39, -v13, v38, v31
	v_fmac_f32_e32 v38, v39, v20
	v_fma_f32 v13, -v13, v38, v31
	v_div_fmas_f32 v13, v13, v20, v38
	v_div_fixup_f32 v2, v13, v2, 1.0
	v_cmp_ge_u32_e32 vcc, v21, v27
	s_waitcnt lgkmcnt(0)
	v_lshlrev_b32_e32 v34, 16, v22
	v_and_b32_e32 v35, 0xffff0000, v22
	v_lshlrev_b32_e32 v22, 16, v23
	v_and_b32_e32 v23, 0xffff0000, v23
	v_lshlrev_b32_e32 v36, 16, v24
	v_and_b32_e32 v37, 0xffff0000, v24
	v_lshlrev_b32_e32 v24, 16, v25
	v_and_b32_e32 v25, 0xffff0000, v25
	v_pk_add_f32 v[4:5], v[4:5], v[22:23]
	v_pk_add_f32 v[6:7], v[6:7], v[24:25]
	v_xor_b32_e32 v23, 0x80000000, v23
	v_xor_b32_e32 v22, 0x80000000, v22
	v_xor_b32_e32 v25, 0x80000000, v25
	v_xor_b32_e32 v24, 0x80000000, v24
	v_pk_add_f32 v[8:9], v[8:9], v[34:35]
	v_pk_add_f32 v[10:11], v[10:11], v[36:37]
	v_pk_fma_f32 v[38:39], v[2:3], v[4:5], v[22:23] op_sel_hi:[0,1,1]
	v_xor_b32_e32 v23, 0x80000000, v35
	v_xor_b32_e32 v22, 0x80000000, v34
	v_pk_fma_f32 v[34:35], v[2:3], v[6:7], v[24:25] op_sel_hi:[0,1,1]
	v_xor_b32_e32 v25, 0x80000000, v37
	v_xor_b32_e32 v24, 0x80000000, v36
	v_pk_fma_f32 v[22:23], v[2:3], v[8:9], v[22:23] op_sel_hi:[0,1,1]
	v_pk_fma_f32 v[24:25], v[2:3], v[10:11], v[24:25] op_sel_hi:[0,1,1]
	v_cvt_pk_bf16_f32 v22, v22, v23
	v_cvt_pk_bf16_f32 v23, v38, v39
	v_cvt_pk_bf16_f32 v24, v24, v25
	v_cvt_pk_bf16_f32 v25, v34, v35
	global_store_dwordx4 v[32:33], v[22:25], off
	s_and_saveexec_b64 s[6:7], vcc
	s_cbranch_execz .LBB0_591
	v_sub_u32_e32 v2, v12, v27
	v_or_b32_e32 v12, 1, v2
	v_ashrrev_i32_e32 v13, 31, v12
	v_lshlrev_b64 v[12:13], 11, v[12:13]
	v_lshl_add_u64 v[12:13], v[14:15], 0, v[12:13]
	v_subrev_u32_e32 v20, s100, v12
	ds_read_b128 v[20:23], v20
	s_waitcnt lgkmcnt(0)
	v_lshlrev_b32_e32 v2, 16, v20
	v_and_b32_e32 v12, 0xffff0000, v20
	v_lshlrev_b32_e32 v13, 16, v21
	v_and_b32_e32 v20, 0xffff0000, v21
	v_lshlrev_b32_e32 v21, 16, v22
	v_and_b32_e32 v22, 0xffff0000, v22
	v_lshlrev_b32_e32 v24, 16, v23
	v_and_b32_e32 v23, 0xffff0000, v23
	v_sub_f32_e32 v5, v5, v20
	v_sub_f32_e32 v4, v4, v13
	v_sub_f32_e32 v9, v9, v12
	v_sub_f32_e32 v8, v8, v2
	v_sub_f32_e32 v7, v7, v23
	v_sub_f32_e32 v6, v6, v24
	v_sub_f32_e32 v11, v11, v22
	v_sub_f32_e32 v10, v10, v21
	s_branch .LBB0_591
; __device__ __forceinline__ size_t oq(size_t c) { asm volatile("" : "+s"(c)); return c; }
; #define PHASE_IDS() const int tid = opaque_tid(), lane = tid & 63, wave = __builtin_amdgcn_readfirstlane(tid >> 6); (void)lane; (void)wave
; __device__ __forceinline__ void hgp_load(const float* G, const bf16_t* Q, const bf16_t* KK, const bf16_t* V, int unit, int wave, int lane, hg_f32x2 (&g)[8], unsigned (&q2)[8], unsigned (&k2)[8], u32x4 (&v4)[2]) {
;     const int b = unit >> 8, h = (unit >> 5) & 7, c = unit & 31;
;     const size_t rb = (size_t)b * SEQ + (size_t)c * 64, colb = (size_t)h * 128 + 2 * lane;
; #pragma unroll
;     for (int i = 0; i < 8; ++i) { const size_t o = (rb + 8 * wave + i) * HDIM + colb; g[i] = *(const hg_f32x2*)(G + o); q2[i] = *(const unsigned*)(Q + o); k2[i] = *(const unsigned*)(KK + o); }
;     const int tid = wave * 64 + lane; const bf16_t* vp = V + (rb + (tid >> 3)) * HDIM + h * 128 + 16 * (tid & 7);
;     v4[0] = *(const u32x4*)vp; v4[1] = *(const u32x4*)(vp + 8);
; __device__ __forceinline__ void p_hgrn_pre(Frame& F) {
;     PHASE_IDS();
;     const bf16_t* Q = (const bf16_t*)(F.ws + oq(WS_Q)); const bf16_t* KK = (const bf16_t*)(F.ws + oq(WS_KK)); const float* G = (const float*)(F.ws + oq(WS_G)); const bf16_t* V = (const bf16_t*)(F.ws + oq(WS_V));
;     unsigned char* IMG = F.ws + oq(WS_HIMG); float* VEC = (float*)(F.ws + oq(WS_HVEC)); unsigned char* UB = F.ws + oq(WS_HU);
;     hg_f32x2 ga[8], gb[8]; unsigned qa[8], qb[8], ka[8], kb[8]; u32x4 va[2], vb[2];
;     int u = blockIdx.x;
;     if (u < 1024) hgp_load(G, Q, KK, V, u, wave, lane, ga, qa, ka, va);
;     while (u < 1024) {
;         const int u2 = u + F.G;
;         if (u2 < 1024) hgp_load(G, Q, KK, V, u2, wave, lane, gb, qb, kb, vb);
.LBB0_610:
	s_or_b64 exec, exec, s[0:1]
	s_waitcnt lgkmcnt(0)
	s_barrier
	v_readlane_b32 s22, v245, 59
	v_mov_b32_e32 v12, v0
	v_readlane_b32 s23, v245, 60
	s_mov_b64 s[0:1], 0x29000000
	v_readfirstlane_b32 s33, v12
	s_mov_b64 s[4:5], 0x2a000000
	s_mov_b64 s[6:7], 0x2c000000
	s_mov_b64 s[14:15], 0x2b000000
	s_mov_b64 s[18:19], 0x49c00000
	s_mov_b64 s[16:17], 0x4d000000
	s_mov_b64 s[20:21], 0x37000000
	s_andn2_b64 vcc, exec, s[22:23]
	s_cbranch_vccnz .LBB0_624
	s_add_u32 s0, s54, s0
	s_addc_u32 s1, s55, s1
	s_add_u32 s4, s54, s4
	s_addc_u32 s5, s55, s5
	s_add_u32 s6, s54, s6
	s_addc_u32 s7, s55, s7
	s_add_u32 s14, s54, s14
	s_addc_u32 s15, s55, s15
	s_add_u32 s30, s54, s18
	s_addc_u32 s31, s55, s19
	s_add_u32 s24, s54, s20
	s_addc_u32 s25, s55, s21
	s_add_u32 s26, s54, s16
	s_addc_u32 s27, s55, s17
	s_ashr_i32 s34, s33, 6
	s_lshl_b32 s16, s34, 3
	s_ashr_i32 s17, s16, 31
	v_readlane_b32 s20, v245, 61
	v_and_b32_e32 v13, 63, v12
	v_readlane_b32 s21, v245, 62
	s_add_u32 s18, s20, s16
	v_lshlrev_b32_e32 v61, 1, v13
	v_readlane_b32 s22, v245, 63
	s_addc_u32 s19, s21, s17
	s_lshl_b64 s[18:19], s[18:19], 10
	v_or_b32_e32 v2, s22, v61
	s_waitcnt lgkmcnt(0)
	v_or_b32_e32 v4, s18, v2
	v_mov_b32_e32 v5, s19
	v_lshlrev_b64 v[6:7], 2, v[4:5]
	v_lshl_add_u64 v[8:9], s[6:7], 0, v[6:7]
	v_lshlrev_b64 v[10:11], 1, v[4:5]
	v_lshl_add_u64 v[14:15], s[0:1], 0, v[10:11]
	v_lshl_add_u64 v[10:11], s[4:5], 0, v[10:11]
	v_or_b32_e32 v6, 0x1000, v6
	global_load_dwordx2 v[52:53], v[8:9], off
	global_load_dword v96, v[14:15], off
	global_load_dword v97, v[10:11], off
	global_load_dword v98, v[10:11], off offset:2048
	global_load_dword v99, v[14:15], off offset:2048
	v_or_b32_e32 v8, 0x800, v4
	v_mov_b32_e32 v9, s19
	v_lshl_add_u64 v[6:7], s[6:7], 0, v[6:7]
	v_lshl_add_u64 v[10:11], v[8:9], 2, s[6:7]
	v_lshlrev_b64 v[8:9], 1, v[8:9]
	v_lshl_add_u64 v[14:15], s[0:1], 0, v[8:9]
	v_lshl_add_u64 v[8:9], s[4:5], 0, v[8:9]
	global_load_dwordx2 v[54:55], v[6:7], off
	global_load_dwordx2 v[56:57], v[10:11], off
	global_load_dword v100, v[14:15], off
	global_load_dword v101, v[8:9], off
	v_or_b32_e32 v6, 0xc00, v4
	v_mov_b32_e32 v7, s19
	v_lshl_add_u64 v[8:9], v[6:7], 2, s[6:7]
	v_lshlrev_b64 v[6:7], 1, v[6:7]
	v_lshl_add_u64 v[10:11], s[0:1], 0, v[6:7]
	v_lshl_add_u64 v[6:7], s[4:5], 0, v[6:7]
	v_or_b32_e32 v14, 0x1000, v4
	v_mov_b32_e32 v15, s19
	v_lshl_add_u64 v[16:17], v[14:15], 2, s[6:7]
	global_load_dwordx2 v[62:63], v[8:9], off
	global_load_dword v102, v[10:11], off
	global_load_dword v103, v[6:7], off
	global_load_dwordx2 v[64:65], v[16:17], off
	v_lshlrev_b64 v[6:7], 1, v[14:15]
	v_or_b32_e32 v10, 0x1400, v4
	v_mov_b32_e32 v11, s19
	v_lshl_add_u64 v[8:9], s[0:1], 0, v[6:7]
	v_lshl_add_u64 v[6:7], s[4:5], 0, v[6:7]
	v_lshl_add_u64 v[14:15], v[10:11], 2, s[6:7]
	v_lshlrev_b64 v[10:11], 1, v[10:11]
	v_mov_b32_e32 v2, s33
	s_movk_i32 s18, 0xffc0
	v_lshl_add_u64 v[16:17], s[0:1], 0, v[10:11]
	v_lshl_add_u64 v[10:11], s[4:5], 0, v[10:11]
	global_load_dword v104, v[8:9], off
	global_load_dword v105, v[6:7], off
	global_load_dwordx2 v[70:71], v[14:15], off
	global_load_dword v106, v[16:17], off
	global_load_dword v107, v[10:11], off
	v_or_b32_e32 v6, 0x1800, v4
	v_mov_b32_e32 v7, s19
	v_bfi_b32 v2, s18, v2, v12
	v_lshl_add_u64 v[8:9], v[6:7], 2, s[6:7]
	v_lshlrev_b64 v[6:7], 1, v[6:7]
	v_or_b32_e32 v4, 0x1c00, v4
	v_ashrrev_i32_e32 v58, 3, v2
	v_lshl_add_u64 v[10:11], s[0:1], 0, v[6:7]
	v_lshl_add_u64 v[14:15], v[4:5], 2, s[6:7]
	v_lshlrev_b64 v[4:5], 1, v[4:5]
	v_ashrrev_i32_e32 v59, 31, v58
	v_lshl_add_u64 v[6:7], s[4:5], 0, v[6:7]
	global_load_dwordx2 v[72:73], v[8:9], off
	global_load_dword v108, v[10:11], off
	global_load_dword v109, v[6:7], off
	global_load_dwordx2 v[76:77], v[14:15], off
	v_lshl_add_u64 v[8:9], s[0:1], 0, v[4:5]
	v_lshl_add_u64 v[10:11], s[4:5], 0, v[4:5]
	v_lshl_add_u64 v[4:5], s[20:21], 0, v[58:59]
	v_lshlrev_b64 v[4:5], 11, v[4:5]
	v_lshlrev_b32_e32 v2, 4, v12
	v_lshl_add_u64 v[4:5], s[14:15], 0, v[4:5]
	s_lshl_b32 s94, s22, 1
	v_and_b32_e32 v60, 0x70, v2
	v_lshl_add_u64 v[4:5], v[4:5], 0, s[94:95]
	v_lshlrev_b32_e32 v2, 1, v60
	v_lshl_add_u64 v[14:15], v[4:5], 0, v[2:3]
	global_load_dwordx4 v[4:7], v[14:15], off offset:16
	global_load_dword v118, v[8:9], off
	global_load_dword v121, v[10:11], off
	s_nop 0
	global_load_dwordx4 v[8:11], v[14:15], off
	s_and_b32 s35, s33, 0xffffffc0
	s_lshl_b32 s36, s34, 9
	s_cmp_gt_i32 s34, 0
	s_cselect_b64 s[40:41], -1, 0
	s_cmp_gt_i32 s34, 1
	s_cselect_b64 s[42:43], -1, 0
	s_cmp_gt_i32 s34, 2
	s_cselect_b64 s[44:45], -1, 0
	s_cmp_gt_i32 s34, 3
	s_cselect_b64 s[46:47], -1, 0
	s_cmp_gt_i32 s34, 4
	s_cselect_b64 s[48:49], -1, 0
	s_cmp_gt_i32 s34, 5
	s_cselect_b64 s[50:51], -1, 0
	s_cmp_gt_i32 s34, 6
	v_lshlrev_b32_e32 v66, 3, v13
	v_lshlrev_b32_e32 v14, 5, v12
	s_cselect_b64 s[52:53], -1, 0
	s_cmp_gt_i32 s34, 7
	v_lshlrev_b32_e32 v68, 2, v13
	s_mul_i32 s18, s34, 0x880
	v_bfe_u32 v13, v12, 2, 4
	v_lshrrev_b32_e32 v15, 1, v12
	v_lshlrev_b32_e32 v12, 7, v12
	s_cselect_b64 s[54:55], -1, 0
	s_add_i32 s20, s18, 0x110
	s_add_i32 s22, s18, 0x220
	s_add_i32 s58, s18, 0x330
	s_add_i32 s60, s18, 0x440
	s_add_i32 s62, s18, 0x550
	s_add_i32 s64, s18, 0x660
	s_add_i32 s66, s18, 0x770
	v_and_b32_e32 v12, 0x780, v12
	s_ashr_i32 s19, s18, 31
	s_ashr_i32 s21, s20, 31
	s_ashr_i32 s23, s22, 31
	s_ashr_i32 s59, s58, 31
	s_ashr_i32 s61, s60, 31
	s_ashr_i32 s63, s62, 31
	s_ashr_i32 s65, s64, 31
	s_ashr_i32 s67, s66, 31
	v_and_b32_e32 v17, 12, v13
	v_lshl_add_u32 v12, s34, 4, v12
	s_cmp_lt_u32 s33, 64
	v_mov_b32_e32 v67, v3
	v_and_b32_e32 v15, 24, v15
	v_or_b32_e32 v12, v12, v17
	s_cselect_b64 s[68:69], -1, 0
	v_lshl_add_u64 v[74:75], s[26:27], 0, v[66:67]
	v_and_or_b32 v15, v13, 3, v15
	s_lshl_b32 s26, s34, 5
	v_ashrrev_i32_e32 v13, 31, v12
	s_movk_i32 s10, 0x110
	v_and_b32_e32 v16, 24, v66
	v_lshl_add_u64 v[78:79], v[12:13], 1, s[24:25]
	s_add_i32 s24, s26, 0
	v_mul_lo_u32 v2, v58, s10
	v_mul_u32_u24_e32 v67, 0x110, v15
	v_mad_u32_u24 v15, v15, s10, v218
	v_add_u32_e32 v12, s24, v16
	s_add_i32 s24, s35, 0
	v_lshlrev_b32_e32 v13, 2, v17
	v_readlane_b32 s10, v242, 18
	v_add_u32_e32 v113, s24, v13
	s_add_i32 s24, s10, s35
	v_and_b32_e32 v14, 0xe0, v14
	v_add_u32_e32 v2, 0, v2
	v_add_u32_e32 v110, 0, v66
	v_add_u32_e32 v112, 0, v16
	v_add_u32_e32 v115, s24, v13
	v_readlane_b32 s24, v242, 12
	v_mov_b32_e32 v69, v3
	s_add_i32 s33, s36, 0
	v_sub_u32_e32 v111, v110, v68
	v_add_u32_e32 v114, s10, v66
	v_mov_b32_e32 v116, s24
	v_add_u32_e32 v117, v112, v15
	v_add_u32_e32 v119, v2, v14
	v_add_u32_e32 v120, v12, v67
	v_readlane_b32 s34, v242, 7
	s_mov_b32 s70, s2
	s_branch .LBB0_614
